# v49 + grid-barrier pollers use s_sleep 4 instead of 1
# speedup vs baseline: 1.0047x; 1.0047x over previous
.LBB0_14:
	s_sleep 4
	global_load_dword v3, v0, s[2:3] offset:32 sc1
	s_waitcnt vmcnt(0)
	v_and_b32_e32 v3, 0xffff0000, v3
	v_cmp_ne_u32_e32 vcc, v3, v2
	s_or_b64 s[4:5], vcc, s[4:5]
	s_andn2_b64 exec, exec, s[4:5]
	s_cbranch_execnz .LBB0_14

.LBB0_115:
	global_load_dword v15, v16, s[4:5] sc1
	s_waitcnt lgkmcnt(0)
	global_load_dword v0, v16, s[6:7] sc1
	global_load_dword v1, v16, s[8:9] sc1
	global_load_dword v2, v16, s[10:11] sc1
	global_load_dword v3, v16, s[12:13] sc1
	global_load_dword v4, v16, s[14:15] sc1
	global_load_dword v5, v16, s[16:17] sc1
	global_load_dword v6, v16, s[18:19] sc1
	global_load_dword v7, v16, s[20:21] sc1
	global_load_dword v8, v16, s[22:23] sc1
	global_load_dword v9, v16, s[24:25] sc1
	global_load_dword v10, v16, s[26:27] sc1
	global_load_dword v11, v16, s[28:29] sc1
	global_load_dword v12, v16, s[30:31] sc1
	global_load_dword v13, v16, s[34:35] sc1
	global_load_dword v14, v16, s[36:37] sc1
	s_mov_b64 s[38:39], -1
	s_mov_b64 s[40:41], -1
	s_waitcnt vmcnt(14)
	v_add_u32_e32 v17, v0, v15
	s_waitcnt vmcnt(13)
	v_add_u32_e32 v17, v17, v1
	s_waitcnt vmcnt(12)
	v_add_u32_e32 v17, v17, v2
	s_waitcnt vmcnt(11)
	v_add_u32_e32 v17, v17, v3
	s_waitcnt vmcnt(10)
	v_add_u32_e32 v17, v17, v4
	s_waitcnt vmcnt(9)
	v_add_u32_e32 v17, v17, v5
	s_waitcnt vmcnt(8)
	v_add_u32_e32 v17, v17, v6
	s_waitcnt vmcnt(7)
	v_add_u32_e32 v17, v17, v7
	s_waitcnt vmcnt(6)
	v_add_u32_e32 v17, v17, v8
	s_waitcnt vmcnt(5)
	v_add_u32_e32 v17, v17, v9
	s_waitcnt vmcnt(4)
	v_add_u32_e32 v17, v17, v10
	s_waitcnt vmcnt(3)
	v_add_u32_e32 v17, v17, v11
	s_waitcnt vmcnt(2)
	v_add_u32_e32 v17, v17, v12
	s_waitcnt vmcnt(1)
	v_add_u32_e32 v17, v17, v13
	s_waitcnt vmcnt(0)
	v_add_u32_e32 v17, v17, v14
	v_cmp_eq_u32_e32 vcc, s33, v17
	s_cbranch_vccnz .LBB0_114
	s_and_b32 s38, s44, 0xff
	s_cmp_eq_u32 s38, 0
	s_mov_b64 s[38:39], -1
	s_mov_b64 s[42:43], -1
	s_sleep 4
	s_cbranch_scc0 .LBB0_119
	global_load_dword v17, v16, s[2:3] sc1
	s_waitcnt vmcnt(0)
	v_cmp_eq_u32_e32 vcc, 0, v17
	s_cbranch_vccnz .LBB0_121
	s_mov_b64 s[42:43], 0

.LBB0_133:
	s_and_b32 s18, s22, 0xff
	s_mov_b64 s[16:17], -1
	s_cmp_lg_u32 s18, 0
	s_mov_b64 s[20:21], -1
	s_sleep 4
	s_cbranch_scc1 .LBB0_136
	global_load_dword v2, v0, s[8:9] sc1
	s_waitcnt vmcnt(0)
	v_cmp_eq_u32_e32 vcc, 0, v2
	s_cbranch_vccnz .LBB0_138
	s_mov_b64 s[20:21], 0
	s_mov_b64 s[18:19], -1

.LBB0_150:
	s_and_b32 s16, s22, 0xff
	s_cmp_lg_u32 s16, 0
	s_mov_b64 s[18:19], -1
	s_sleep 4
	s_cbranch_scc1 .LBB0_153
	global_load_dword v1, v0, s[8:9] sc1
	s_waitcnt vmcnt(0)
	v_cmp_eq_u32_e32 vcc, 0, v1
	s_cbranch_vccnz .LBB0_155
	s_mov_b64 s[18:19], 0
	s_mov_b64 s[16:17], -1

.LBB0_571:
	global_load_dword v15, v16, s[6:7] sc1
	s_waitcnt lgkmcnt(0)
	global_load_dword v0, v16, s[8:9] sc1
	global_load_dword v1, v16, s[10:11] sc1
	global_load_dword v2, v16, s[12:13] sc1
	global_load_dword v3, v16, s[14:15] sc1
	global_load_dword v4, v16, s[16:17] sc1
	global_load_dword v5, v16, s[18:19] sc1
	global_load_dword v6, v16, s[20:21] sc1
	global_load_dword v7, v16, s[22:23] sc1
	global_load_dword v8, v16, s[24:25] sc1
	global_load_dword v9, v16, s[26:27] sc1
	global_load_dword v10, v16, s[28:29] sc1
	global_load_dword v11, v16, s[30:31] sc1
	global_load_dword v12, v16, s[34:35] sc1
	global_load_dword v13, v16, s[36:37] sc1
	global_load_dword v14, v16, s[38:39] sc1
	s_mov_b64 s[40:41], -1
	s_mov_b64 s[42:43], -1
	s_waitcnt vmcnt(14)
	v_add_u32_e32 v17, v0, v15
	s_waitcnt vmcnt(13)
	v_add_u32_e32 v17, v17, v1
	s_waitcnt vmcnt(12)
	v_add_u32_e32 v17, v17, v2
	s_waitcnt vmcnt(11)
	v_add_u32_e32 v17, v17, v3
	s_waitcnt vmcnt(10)
	v_add_u32_e32 v17, v17, v4
	s_waitcnt vmcnt(9)
	v_add_u32_e32 v17, v17, v5
	s_waitcnt vmcnt(8)
	v_add_u32_e32 v17, v17, v6
	s_waitcnt vmcnt(7)
	v_add_u32_e32 v17, v17, v7
	s_waitcnt vmcnt(6)
	v_add_u32_e32 v17, v17, v8
	s_waitcnt vmcnt(5)
	v_add_u32_e32 v17, v17, v9
	s_waitcnt vmcnt(4)
	v_add_u32_e32 v17, v17, v10
	s_waitcnt vmcnt(3)
	v_add_u32_e32 v17, v17, v11
	s_waitcnt vmcnt(2)
	v_add_u32_e32 v17, v17, v12
	s_waitcnt vmcnt(1)
	v_add_u32_e32 v17, v17, v13
	s_waitcnt vmcnt(0)
	v_add_u32_e32 v17, v17, v14
	v_cmp_eq_u32_e32 vcc, s33, v17
	s_cbranch_vccnz .LBB0_570
	s_and_b32 s40, s46, 0xff
	s_cmp_eq_u32 s40, 0
	s_mov_b64 s[40:41], -1
	s_mov_b64 s[44:45], -1
	s_sleep 4
	s_cbranch_scc0 .LBB0_575
	global_load_dword v17, v16, s[2:3] sc1
	s_waitcnt vmcnt(0)
	v_cmp_eq_u32_e32 vcc, 0, v17
	s_cbranch_vccnz .LBB0_577
	s_mov_b64 s[44:45], 0

.LBB0_589:
	s_and_b32 s20, s24, 0xff
	s_mov_b64 s[18:19], -1
	s_cmp_lg_u32 s20, 0
	s_mov_b64 s[22:23], -1
	s_sleep 4
	s_cbranch_scc1 .LBB0_592
	global_load_dword v2, v0, s[10:11] sc1
	s_waitcnt vmcnt(0)
	v_cmp_eq_u32_e32 vcc, 0, v2
	s_cbranch_vccnz .LBB0_594
	s_mov_b64 s[22:23], 0
	s_mov_b64 s[20:21], -1

.LBB0_606:
	s_and_b32 s18, s24, 0xff
	s_cmp_lg_u32 s18, 0
	s_mov_b64 s[20:21], -1
	s_sleep 4
	s_cbranch_scc1 .LBB0_609
	global_load_dword v1, v0, s[10:11] sc1
	s_waitcnt vmcnt(0)
	v_cmp_eq_u32_e32 vcc, 0, v1
	s_cbranch_vccnz .LBB0_611
	s_mov_b64 s[20:21], 0
	s_mov_b64 s[18:19], -1

.LBB0_658:
	global_load_dword v15, v16, s[12:13] sc1
	s_waitcnt lgkmcnt(0)
	global_load_dword v0, v16, s[14:15] sc1
	global_load_dword v1, v16, s[16:17] sc1
	global_load_dword v2, v16, s[18:19] sc1
	global_load_dword v3, v16, s[20:21] sc1
	global_load_dword v4, v16, s[22:23] sc1
	global_load_dword v5, v16, s[24:25] sc1
	global_load_dword v6, v16, s[26:27] sc1
	global_load_dword v7, v16, s[28:29] sc1
	global_load_dword v8, v16, s[30:31] sc1
	global_load_dword v9, v16, s[34:35] sc1
	global_load_dword v10, v16, s[36:37] sc1
	global_load_dword v11, v16, s[38:39] sc1
	global_load_dword v12, v16, s[40:41] sc1
	global_load_dword v13, v16, s[42:43] sc1
	global_load_dword v14, v16, s[44:45] sc1
	s_mov_b64 s[46:47], -1
	s_mov_b64 s[48:49], -1
	s_waitcnt vmcnt(14)
	v_add_u32_e32 v17, v0, v15
	s_waitcnt vmcnt(13)
	v_add_u32_e32 v17, v17, v1
	s_waitcnt vmcnt(12)
	v_add_u32_e32 v17, v17, v2
	s_waitcnt vmcnt(11)
	v_add_u32_e32 v17, v17, v3
	s_waitcnt vmcnt(10)
	v_add_u32_e32 v17, v17, v4
	s_waitcnt vmcnt(9)
	v_add_u32_e32 v17, v17, v5
	s_waitcnt vmcnt(8)
	v_add_u32_e32 v17, v17, v6
	s_waitcnt vmcnt(7)
	v_add_u32_e32 v17, v17, v7
	s_waitcnt vmcnt(6)
	v_add_u32_e32 v17, v17, v8
	s_waitcnt vmcnt(5)
	v_add_u32_e32 v17, v17, v9
	s_waitcnt vmcnt(4)
	v_add_u32_e32 v17, v17, v10
	s_waitcnt vmcnt(3)
	v_add_u32_e32 v17, v17, v11
	s_waitcnt vmcnt(2)
	v_add_u32_e32 v17, v17, v12
	s_waitcnt vmcnt(1)
	v_add_u32_e32 v17, v17, v13
	s_waitcnt vmcnt(0)
	v_add_u32_e32 v17, v17, v14
	v_cmp_eq_u32_e32 vcc, s52, v17
	s_cbranch_vccnz .LBB0_657
	s_and_b32 s46, s53, 0xff
	s_cmp_eq_u32 s46, 0
	s_mov_b64 s[46:47], -1
	s_mov_b64 s[50:51], -1
	s_sleep 4
	s_cbranch_scc0 .LBB0_662
	global_load_dword v17, v16, s[10:11] sc1
	s_waitcnt vmcnt(0)
	v_cmp_eq_u32_e32 vcc, 0, v17
	s_cbranch_vccnz .LBB0_664
	s_mov_b64 s[50:51], 0

.LBB0_676:
	s_and_b32 s26, s30, 0xff
	s_mov_b64 s[24:25], -1
	s_cmp_lg_u32 s26, 0
	s_mov_b64 s[28:29], -1
	s_sleep 4
	s_cbranch_scc1 .LBB0_679
	global_load_dword v2, v0, s[16:17] sc1
	s_waitcnt vmcnt(0)
	v_cmp_eq_u32_e32 vcc, 0, v2
	s_cbranch_vccnz .LBB0_681
	s_mov_b64 s[28:29], 0
	s_mov_b64 s[26:27], -1

.LBB0_693:
	s_and_b32 s24, s30, 0xff
	s_cmp_lg_u32 s24, 0
	s_mov_b64 s[26:27], -1
	s_sleep 4
	s_cbranch_scc1 .LBB0_696
	global_load_dword v1, v0, s[16:17] sc1
	s_waitcnt vmcnt(0)
	v_cmp_eq_u32_e32 vcc, 0, v1
	s_cbranch_vccnz .LBB0_698
	s_mov_b64 s[26:27], 0
	s_mov_b64 s[24:25], -1

.LBB0_848:
	global_load_dword v15, v16, s[6:7] sc1
	s_waitcnt lgkmcnt(0)
	global_load_dword v0, v16, s[8:9] sc1
	global_load_dword v1, v16, s[10:11] sc1
	global_load_dword v2, v16, s[16:17] sc1
	global_load_dword v3, v16, s[18:19] sc1
	global_load_dword v4, v16, s[20:21] sc1
	global_load_dword v5, v16, s[22:23] sc1
	global_load_dword v6, v16, s[24:25] sc1
	global_load_dword v7, v16, s[26:27] sc1
	global_load_dword v8, v16, s[28:29] sc1
	global_load_dword v9, v16, s[30:31] sc1
	global_load_dword v10, v16, s[34:35] sc1
	global_load_dword v11, v16, s[36:37] sc1
	global_load_dword v12, v16, s[38:39] sc1
	global_load_dword v13, v16, s[40:41] sc1
	global_load_dword v14, v16, s[42:43] sc1
	s_mov_b64 s[44:45], -1
	s_mov_b64 s[46:47], -1
	s_waitcnt vmcnt(14)
	v_add_u32_e32 v17, v0, v15
	s_waitcnt vmcnt(13)
	v_add_u32_e32 v17, v17, v1
	s_waitcnt vmcnt(12)
	v_add_u32_e32 v17, v17, v2
	s_waitcnt vmcnt(11)
	v_add_u32_e32 v17, v17, v3
	s_waitcnt vmcnt(10)
	v_add_u32_e32 v17, v17, v4
	s_waitcnt vmcnt(9)
	v_add_u32_e32 v17, v17, v5
	s_waitcnt vmcnt(8)
	v_add_u32_e32 v17, v17, v6
	s_waitcnt vmcnt(7)
	v_add_u32_e32 v17, v17, v7
	s_waitcnt vmcnt(6)
	v_add_u32_e32 v17, v17, v8
	s_waitcnt vmcnt(5)
	v_add_u32_e32 v17, v17, v9
	s_waitcnt vmcnt(4)
	v_add_u32_e32 v17, v17, v10
	s_waitcnt vmcnt(3)
	v_add_u32_e32 v17, v17, v11
	s_waitcnt vmcnt(2)
	v_add_u32_e32 v17, v17, v12
	s_waitcnt vmcnt(1)
	v_add_u32_e32 v17, v17, v13
	s_waitcnt vmcnt(0)
	v_add_u32_e32 v17, v17, v14
	v_cmp_eq_u32_e32 vcc, s33, v17
	s_cbranch_vccnz .LBB0_847
	s_and_b32 s44, s50, 0xff
	s_cmp_eq_u32 s44, 0
	s_mov_b64 s[44:45], -1
	s_mov_b64 s[48:49], -1
	s_sleep 4
	s_cbranch_scc0 .LBB0_852
	global_load_dword v17, v16, s[4:5] sc1
	s_waitcnt vmcnt(0)
	v_cmp_eq_u32_e32 vcc, 0, v17
	s_cbranch_vccnz .LBB0_854
	s_mov_b64 s[48:49], 0

.LBB0_866:
	s_and_b32 s24, s28, 0xff
	s_mov_b64 s[22:23], -1
	s_cmp_lg_u32 s24, 0
	s_mov_b64 s[26:27], -1
	s_sleep 4
	s_cbranch_scc1 .LBB0_869
	global_load_dword v2, v0, s[10:11] sc1
	s_waitcnt vmcnt(0)
	v_cmp_eq_u32_e32 vcc, 0, v2
	s_cbranch_vccnz .LBB0_871
	s_mov_b64 s[26:27], 0
	s_mov_b64 s[24:25], -1

.LBB0_883:
	s_and_b32 s22, s28, 0xff
	s_cmp_lg_u32 s22, 0
	s_mov_b64 s[24:25], -1
	s_sleep 4
	s_cbranch_scc1 .LBB0_886
	global_load_dword v1, v0, s[10:11] sc1
	s_waitcnt vmcnt(0)
	v_cmp_eq_u32_e32 vcc, 0, v1
	s_cbranch_vccnz .LBB0_888
	s_mov_b64 s[24:25], 0
	s_mov_b64 s[22:23], -1

.LBB0_956:
	global_load_dword v15, v16, s[6:7] sc1
	s_waitcnt lgkmcnt(0)
	global_load_dword v0, v16, s[8:9] sc1
	global_load_dword v1, v16, s[10:11] sc1
	global_load_dword v2, v16, s[16:17] sc1
	global_load_dword v3, v16, s[20:21] sc1
	global_load_dword v4, v16, s[22:23] sc1
	global_load_dword v5, v16, s[24:25] sc1
	global_load_dword v6, v16, s[26:27] sc1
	global_load_dword v7, v16, s[28:29] sc1
	global_load_dword v8, v16, s[30:31] sc1
	global_load_dword v9, v16, s[34:35] sc1
	global_load_dword v10, v16, s[36:37] sc1
	global_load_dword v11, v16, s[38:39] sc1
	global_load_dword v12, v16, s[40:41] sc1
	global_load_dword v13, v16, s[42:43] sc1
	global_load_dword v14, v16, s[44:45] sc1
	s_mov_b64 s[46:47], -1
	s_mov_b64 s[48:49], -1
	s_waitcnt vmcnt(14)
	v_add_u32_e32 v17, v0, v15
	s_waitcnt vmcnt(13)
	v_add_u32_e32 v17, v17, v1
	s_waitcnt vmcnt(12)
	v_add_u32_e32 v17, v17, v2
	s_waitcnt vmcnt(11)
	v_add_u32_e32 v17, v17, v3
	s_waitcnt vmcnt(10)
	v_add_u32_e32 v17, v17, v4
	s_waitcnt vmcnt(9)
	v_add_u32_e32 v17, v17, v5
	s_waitcnt vmcnt(8)
	v_add_u32_e32 v17, v17, v6
	s_waitcnt vmcnt(7)
	v_add_u32_e32 v17, v17, v7
	s_waitcnt vmcnt(6)
	v_add_u32_e32 v17, v17, v8
	s_waitcnt vmcnt(5)
	v_add_u32_e32 v17, v17, v9
	s_waitcnt vmcnt(4)
	v_add_u32_e32 v17, v17, v10
	s_waitcnt vmcnt(3)
	v_add_u32_e32 v17, v17, v11
	s_waitcnt vmcnt(2)
	v_add_u32_e32 v17, v17, v12
	s_waitcnt vmcnt(1)
	v_add_u32_e32 v17, v17, v13
	s_waitcnt vmcnt(0)
	v_add_u32_e32 v17, v17, v14
	v_cmp_eq_u32_e32 vcc, s33, v17
	s_cbranch_vccnz .LBB0_955
	s_and_b32 s46, s52, 0xff
	s_cmp_eq_u32 s46, 0
	s_mov_b64 s[46:47], -1
	s_mov_b64 s[50:51], -1
	s_sleep 4
	s_cbranch_scc0 .LBB0_960
	global_load_dword v17, v16, s[4:5] sc1
	s_waitcnt vmcnt(0)
	v_cmp_eq_u32_e32 vcc, 0, v17
	s_cbranch_vccnz .LBB0_962
	s_mov_b64 s[50:51], 0

.LBB0_974:
	s_and_b32 s26, s30, 0xff
	s_mov_b64 s[24:25], -1
	s_cmp_lg_u32 s26, 0
	s_mov_b64 s[28:29], -1
	s_sleep 4
	s_cbranch_scc1 .LBB0_977
	global_load_dword v2, v0, s[10:11] sc1
	s_waitcnt vmcnt(0)
	v_cmp_eq_u32_e32 vcc, 0, v2
	s_cbranch_vccnz .LBB0_979
	s_mov_b64 s[28:29], 0
	s_mov_b64 s[26:27], -1

.LBB0_991:
	s_and_b32 s24, s30, 0xff
	s_cmp_lg_u32 s24, 0
	s_mov_b64 s[26:27], -1
	s_sleep 4
	s_cbranch_scc1 .LBB0_994
	global_load_dword v1, v0, s[10:11] sc1
	s_waitcnt vmcnt(0)
	v_cmp_eq_u32_e32 vcc, 0, v1
	s_cbranch_vccnz .LBB0_996
	s_mov_b64 s[26:27], 0
	s_mov_b64 s[24:25], -1

.LBB0_1023:
	global_load_dword v15, v16, s[6:7] sc1
	s_waitcnt lgkmcnt(0)
	global_load_dword v0, v16, s[8:9] sc1
	global_load_dword v1, v16, s[10:11] sc1
	global_load_dword v2, v16, s[18:19] sc1
	global_load_dword v3, v16, s[20:21] sc1
	global_load_dword v4, v16, s[22:23] sc1
	global_load_dword v5, v16, s[24:25] sc1
	global_load_dword v6, v16, s[26:27] sc1
	global_load_dword v7, v16, s[28:29] sc1
	global_load_dword v8, v16, s[30:31] sc1
	global_load_dword v9, v16, s[34:35] sc1
	global_load_dword v10, v16, s[36:37] sc1
	global_load_dword v11, v16, s[38:39] sc1
	global_load_dword v12, v16, s[40:41] sc1
	global_load_dword v13, v16, s[42:43] sc1
	global_load_dword v14, v16, s[44:45] sc1
	s_mov_b64 s[46:47], -1
	s_mov_b64 s[48:49], -1
	s_waitcnt vmcnt(14)
	v_add_u32_e32 v17, v0, v15
	s_waitcnt vmcnt(13)
	v_add_u32_e32 v17, v17, v1
	s_waitcnt vmcnt(12)
	v_add_u32_e32 v17, v17, v2
	s_waitcnt vmcnt(11)
	v_add_u32_e32 v17, v17, v3
	s_waitcnt vmcnt(10)
	v_add_u32_e32 v17, v17, v4
	s_waitcnt vmcnt(9)
	v_add_u32_e32 v17, v17, v5
	s_waitcnt vmcnt(8)
	v_add_u32_e32 v17, v17, v6
	s_waitcnt vmcnt(7)
	v_add_u32_e32 v17, v17, v7
	s_waitcnt vmcnt(6)
	v_add_u32_e32 v17, v17, v8
	s_waitcnt vmcnt(5)
	v_add_u32_e32 v17, v17, v9
	s_waitcnt vmcnt(4)
	v_add_u32_e32 v17, v17, v10
	s_waitcnt vmcnt(3)
	v_add_u32_e32 v17, v17, v11
	s_waitcnt vmcnt(2)
	v_add_u32_e32 v17, v17, v12
	s_waitcnt vmcnt(1)
	v_add_u32_e32 v17, v17, v13
	s_waitcnt vmcnt(0)
	v_add_u32_e32 v17, v17, v14
	v_cmp_eq_u32_e32 vcc, s33, v17
	s_cbranch_vccnz .LBB0_1022
	s_and_b32 s46, s52, 0xff
	s_cmp_eq_u32 s46, 0
	s_mov_b64 s[46:47], -1
	s_mov_b64 s[50:51], -1
	s_sleep 4
	s_cbranch_scc0 .LBB0_1027
	global_load_dword v17, v16, s[4:5] sc1
	s_waitcnt vmcnt(0)
	v_cmp_eq_u32_e32 vcc, 0, v17
	s_cbranch_vccnz .LBB0_1029
	s_mov_b64 s[50:51], 0

.LBB0_1201:
	global_load_dword v15, v16, s[4:5] sc1
	s_waitcnt lgkmcnt(0)
	global_load_dword v0, v16, s[6:7] sc1
	global_load_dword v1, v16, s[8:9] sc1
	global_load_dword v2, v16, s[10:11] sc1
	global_load_dword v3, v16, s[16:17] sc1
	global_load_dword v4, v16, s[18:19] sc1
	global_load_dword v5, v16, s[20:21] sc1
	global_load_dword v6, v16, s[22:23] sc1
	global_load_dword v7, v16, s[24:25] sc1
	global_load_dword v8, v16, s[26:27] sc1
	global_load_dword v9, v16, s[28:29] sc1
	global_load_dword v10, v16, s[30:31] sc1
	global_load_dword v11, v16, s[34:35] sc1
	global_load_dword v12, v16, s[36:37] sc1
	global_load_dword v13, v16, s[38:39] sc1
	global_load_dword v14, v16, s[40:41] sc1
	s_mov_b64 s[42:43], -1
	s_mov_b64 s[44:45], -1
	s_waitcnt vmcnt(14)
	v_add_u32_e32 v17, v0, v15
	s_waitcnt vmcnt(13)
	v_add_u32_e32 v17, v17, v1
	s_waitcnt vmcnt(12)
	v_add_u32_e32 v17, v17, v2
	s_waitcnt vmcnt(11)
	v_add_u32_e32 v17, v17, v3
	s_waitcnt vmcnt(10)
	v_add_u32_e32 v17, v17, v4
	s_waitcnt vmcnt(9)
	v_add_u32_e32 v17, v17, v5
	s_waitcnt vmcnt(8)
	v_add_u32_e32 v17, v17, v6
	s_waitcnt vmcnt(7)
	v_add_u32_e32 v17, v17, v7
	s_waitcnt vmcnt(6)
	v_add_u32_e32 v17, v17, v8
	s_waitcnt vmcnt(5)
	v_add_u32_e32 v17, v17, v9
	s_waitcnt vmcnt(4)
	v_add_u32_e32 v17, v17, v10
	s_waitcnt vmcnt(3)
	v_add_u32_e32 v17, v17, v11
	s_waitcnt vmcnt(2)
	v_add_u32_e32 v17, v17, v12
	s_waitcnt vmcnt(1)
	v_add_u32_e32 v17, v17, v13
	s_waitcnt vmcnt(0)
	v_add_u32_e32 v17, v17, v14
	v_cmp_eq_u32_e32 vcc, s33, v17
	s_cbranch_vccnz .LBB0_1200
	s_and_b32 s42, s48, 0xff
	s_cmp_eq_u32 s42, 0
	s_mov_b64 s[42:43], -1
	s_mov_b64 s[46:47], -1
	s_sleep 4
	s_cbranch_scc0 .LBB0_1205
	global_load_dword v17, v16, s[2:3] sc1
	s_waitcnt vmcnt(0)
	v_cmp_eq_u32_e32 vcc, 0, v17
	s_cbranch_vccnz .LBB0_1207
	s_mov_b64 s[46:47], 0

.LBB0_1219:
	s_and_b32 s22, s26, 0xff
	s_mov_b64 s[20:21], -1
	s_cmp_lg_u32 s22, 0
	s_mov_b64 s[24:25], -1
	s_sleep 4
	s_cbranch_scc1 .LBB0_1222
	global_load_dword v2, v0, s[8:9] sc1
	s_waitcnt vmcnt(0)
	v_cmp_eq_u32_e32 vcc, 0, v2
	s_cbranch_vccnz .LBB0_1224
	s_mov_b64 s[24:25], 0
	s_mov_b64 s[22:23], -1

.LBB0_1236:
	s_and_b32 s20, s26, 0xff
	s_cmp_lg_u32 s20, 0
	s_mov_b64 s[22:23], -1
	s_sleep 4
	s_cbranch_scc1 .LBB0_1239
	global_load_dword v1, v0, s[8:9] sc1
	s_waitcnt vmcnt(0)
	v_cmp_eq_u32_e32 vcc, 0, v1
	s_cbranch_vccnz .LBB0_1241
	s_mov_b64 s[22:23], 0
	s_mov_b64 s[20:21], -1
